# GEMM_UP / GEMM_IN epilogues: the eight per-row rstd LDS reads issued together (was read-wait-use per row), with the store-data hazard padding
# speedup vs baseline: 1.0090x; 1.0027x over previous
; #define LAS __attribute__((address_space(3)))
; __device__ __forceinline__ unsigned pk2(float lo, float hi) { unsigned r; asm volatile("v_cvt_pk_bf16_f32 %0, %1, %2" : "=v"(r) : "v"(lo), "v"(hi)); return r; }
; #define EPI_SYNC() do { asm volatile("s_waitcnt lgkmcnt(0)" ::: "memory"); __builtin_amdgcn_s_barrier(); __builtin_amdgcn_s_barrier(); asm volatile("" ::: "memory"); } while (0)
;     __device__ __forceinline__ void operator()(f32x4 (&acc)[2][2][4][2], const Unit& u, int wr, int wc, int fr, int fq, LAS unsigned char* lds) const {
;     ...
;         {
;             LAS float* cw = (LAS float*)(lds + EPI_CW);
; #pragma unroll
;             for (int i = 0; i < 2; ++i) {
;                 const int e = tid + 512 * i, bj = e >> 9, k = (e >> 7) & 3, c = e & 127;
;                 cw[e] = k < 3 ? w3[k * 2 * DFF + bj * DFF + u.b0 + c] : b3[bj * DFF + u.b0 + c];
;             }
;         }
;         EPI_SYNC();
;         const LAS float* rs = (const LAS float*)(lds + EPI_RS);
;         unsigned pq[2][2][4][2][2];
; #pragma unroll
;         for (int ai = 0; ai < 2; ++ai)
; #pragma unroll
;             for (int m = 0; m < 4; ++m) {
;                 const float r = rs[128 * ai + 64 * wr + 16 * m + fr];
; #pragma unroll
;                 for (int bj = 0; bj < 2; ++bj)
; #pragma unroll
;                     for (int n = 0; n < 2; ++n) {
;                         const f32x4 v = acc[ai][bj][m][n];
;                         pq[ai][bj][m][n][0] = r != 0.f ? pk2(v.x * r, v.y * r) : 0u;
;                         pq[ai][bj][m][n][1] = r != 0.f ? pk2(v.z * r, v.w * r) : 0u;
.LBB0_167:
	s_or_b64 exec, exec, s[0:1]
	v_lshl_add_u32 v23, v25, 2, 0
	v_add_u32_e32 v24, 0, v24
	v_add_u32_e32 v23, 0x21400, v23
	v_lshl_add_u32 v24, v144, 2, v24
	v_add_u32_e32 v146, 0x21000, v24
	s_waitcnt vmcnt(6)
	ds_write2st64_b32 v23, v248, v249 offset1:8
	s_waitcnt lgkmcnt(0)
	s_barrier
	s_barrier
	ds_read_b32 v147, v146
	ds_read_b32 v170, v146 offset:64
	ds_read_b32 v171, v146 offset:128
	ds_read_b32 v172, v146 offset:192
	ds_read_b32 v173, v146 offset:512
	ds_read_b32 v174, v146 offset:576
	ds_read_b32 v175, v146 offset:640
	ds_read_b32 v176, v146 offset:704
	v_mov_b32_e32 v23, 0
	v_mov_b32_e32 v22, 0
	s_waitcnt lgkmcnt(0)
	v_cmp_neq_f32_e32 vcc, 0, v147
	s_and_saveexec_b64 s[0:1], vcc
	s_cbranch_execz .LBB0_169
	v_mul_f32_e32 v22, v131, v147
	v_mul_f32_e32 v24, v130, v147
	v_cvt_pk_bf16_f32 v22, v24, v22

; __device__ __forceinline__ unsigned pk2(float lo, float hi) { unsigned r; asm volatile("v_cvt_pk_bf16_f32 %0, %1, %2" : "=v"(r) : "v"(lo), "v"(hi)); return r; }
;     __device__ __forceinline__ void operator()(f32x4 (&acc)[2][2][4][2], const Unit& u, int wr, int wc, int fr, int fq, LAS unsigned char* lds) const {
;     ...
;             for (int m = 0; m < 4; ++m) {
;                 const float r = rs[128 * ai + 64 * wr + 16 * m + fr];
; #pragma unroll
;                 for (int bj = 0; bj < 2; ++bj)
; #pragma unroll
;                     for (int n = 0; n < 2; ++n) {
;                         const f32x4 v = acc[ai][bj][m][n];
;                         pq[ai][bj][m][n][0] = r != 0.f ? pk2(v.x * r, v.y * r) : 0u;
;                         pq[ai][bj][m][n][1] = r != 0.f ? pk2(v.z * r, v.w * r) : 0u;
.LBB0_183:
	s_or_b64 exec, exec, s[0:1]
	s_nop 1
	v_mov_b32_e32 v124, v170
	v_mov_b32_e32 v122, 0
	v_mov_b32_e32 v123, 0
	s_waitcnt lgkmcnt(0)
	v_cmp_neq_f32_e32 vcc, 0, v124
	s_and_saveexec_b64 s[0:1], vcc
	s_cbranch_execz .LBB0_185
	v_mul_f32_e32 v119, v119, v124
	v_mul_f32_e32 v118, v118, v124
	v_cvt_pk_bf16_f32 v123, v118, v119

; __device__ __forceinline__ unsigned pk2(float lo, float hi) { unsigned r; asm volatile("v_cvt_pk_bf16_f32 %0, %1, %2" : "=v"(r) : "v"(lo), "v"(hi)); return r; }
;     __device__ __forceinline__ void operator()(f32x4 (&acc)[2][2][4][2], const Unit& u, int wr, int wc, int fr, int fq, LAS unsigned char* lds) const {
;     ...
;             for (int m = 0; m < 4; ++m) {
;                 const float r = rs[128 * ai + 64 * wr + 16 * m + fr];
; #pragma unroll
;                 for (int bj = 0; bj < 2; ++bj)
; #pragma unroll
;                     for (int n = 0; n < 2; ++n) {
;                         const f32x4 v = acc[ai][bj][m][n];
;                         pq[ai][bj][m][n][0] = r != 0.f ? pk2(v.x * r, v.y * r) : 0u;
;                         pq[ai][bj][m][n][1] = r != 0.f ? pk2(v.z * r, v.w * r) : 0u;
.LBB0_199:
	s_or_b64 exec, exec, s[0:1]
	s_nop 1
	v_mov_b32_e32 v108, v171
	v_mov_b32_e32 v106, 0
	v_mov_b32_e32 v107, 0
	s_waitcnt lgkmcnt(0)
	v_cmp_neq_f32_e32 vcc, 0, v108
	s_and_saveexec_b64 s[0:1], vcc
	s_cbranch_execz .LBB0_201
	v_mul_f32_e32 v103, v103, v108
	v_mul_f32_e32 v102, v102, v108
	v_cvt_pk_bf16_f32 v107, v102, v103

; __device__ __forceinline__ unsigned pk2(float lo, float hi) { unsigned r; asm volatile("v_cvt_pk_bf16_f32 %0, %1, %2" : "=v"(r) : "v"(lo), "v"(hi)); return r; }
;     __device__ __forceinline__ void operator()(f32x4 (&acc)[2][2][4][2], const Unit& u, int wr, int wc, int fr, int fq, LAS unsigned char* lds) const {
;     ...
;             for (int m = 0; m < 4; ++m) {
;                 const float r = rs[128 * ai + 64 * wr + 16 * m + fr];
; #pragma unroll
;                 for (int bj = 0; bj < 2; ++bj)
; #pragma unroll
;                     for (int n = 0; n < 2; ++n) {
;                         const f32x4 v = acc[ai][bj][m][n];
;                         pq[ai][bj][m][n][0] = r != 0.f ? pk2(v.x * r, v.y * r) : 0u;
;                         pq[ai][bj][m][n][1] = r != 0.f ? pk2(v.z * r, v.w * r) : 0u;
.LBB0_215:
	s_or_b64 exec, exec, s[0:1]
	s_nop 1
	v_mov_b32_e32 v96, v172
	v_mov_b32_e32 v39, 0
	v_mov_b32_e32 v38, 0
	s_waitcnt lgkmcnt(0)
	v_cmp_neq_f32_e32 vcc, 0, v96
	s_and_saveexec_b64 s[0:1], vcc
	s_cbranch_execz .LBB0_217
	v_mul_f32_e32 v38, v91, v96
	v_mul_f32_e32 v40, v90, v96
	v_cvt_pk_bf16_f32 v38, v40, v38

; __device__ __forceinline__ unsigned pk2(float lo, float hi) { unsigned r; asm volatile("v_cvt_pk_bf16_f32 %0, %1, %2" : "=v"(r) : "v"(lo), "v"(hi)); return r; }
;     __device__ __forceinline__ void operator()(f32x4 (&acc)[2][2][4][2], const Unit& u, int wr, int wc, int fr, int fq, LAS unsigned char* lds) const {
;     ...
;             for (int m = 0; m < 4; ++m) {
;                 const float r = rs[128 * ai + 64 * wr + 16 * m + fr];
; #pragma unroll
;                 for (int bj = 0; bj < 2; ++bj)
; #pragma unroll
;                     for (int n = 0; n < 2; ++n) {
;                         const f32x4 v = acc[ai][bj][m][n];
;                         pq[ai][bj][m][n][0] = r != 0.f ? pk2(v.x * r, v.y * r) : 0u;
;                         pq[ai][bj][m][n][1] = r != 0.f ? pk2(v.z * r, v.w * r) : 0u;
.LBB0_231:
	s_or_b64 exec, exec, s[0:1]
	s_nop 1
	v_mov_b32_e32 v86, v173
	v_mov_b32_e32 v7, 0
	v_mov_b32_e32 v6, 0
	s_waitcnt lgkmcnt(0)
	v_cmp_neq_f32_e32 vcc, 0, v86
	s_and_saveexec_b64 s[0:1], vcc
	s_cbranch_execz .LBB0_233
	v_mul_f32_e32 v6, v83, v86
	v_mul_f32_e32 v8, v82, v86
	v_cvt_pk_bf16_f32 v6, v8, v6

; __device__ __forceinline__ unsigned pk2(float lo, float hi) { unsigned r; asm volatile("v_cvt_pk_bf16_f32 %0, %1, %2" : "=v"(r) : "v"(lo), "v"(hi)); return r; }
;     __device__ __forceinline__ void operator()(f32x4 (&acc)[2][2][4][2], const Unit& u, int wr, int wc, int fr, int fq, LAS unsigned char* lds) const {
;     ...
;             for (int m = 0; m < 4; ++m) {
;                 const float r = rs[128 * ai + 64 * wr + 16 * m + fr];
; #pragma unroll
;                 for (int bj = 0; bj < 2; ++bj)
; #pragma unroll
;                     for (int n = 0; n < 2; ++n) {
;                         const f32x4 v = acc[ai][bj][m][n];
;                         pq[ai][bj][m][n][0] = r != 0.f ? pk2(v.x * r, v.y * r) : 0u;
;                         pq[ai][bj][m][n][1] = r != 0.f ? pk2(v.z * r, v.w * r) : 0u;
.LBB0_247:
	s_or_b64 exec, exec, s[0:1]
	s_nop 1
	v_mov_b32_e32 v76, v174
	v_mov_b32_e32 v74, 0
	v_mov_b32_e32 v75, 0
	s_waitcnt lgkmcnt(0)
	v_cmp_neq_f32_e32 vcc, 0, v76
	s_and_saveexec_b64 s[0:1], vcc
	s_cbranch_execz .LBB0_249
	v_mul_f32_e32 v71, v71, v76
	v_mul_f32_e32 v70, v70, v76
	v_cvt_pk_bf16_f32 v75, v70, v71

; __device__ __forceinline__ unsigned pk2(float lo, float hi) { unsigned r; asm volatile("v_cvt_pk_bf16_f32 %0, %1, %2" : "=v"(r) : "v"(lo), "v"(hi)); return r; }
;     __device__ __forceinline__ void operator()(f32x4 (&acc)[2][2][4][2], const Unit& u, int wr, int wc, int fr, int fq, LAS unsigned char* lds) const {
;     ...
;             for (int m = 0; m < 4; ++m) {
;                 const float r = rs[128 * ai + 64 * wr + 16 * m + fr];
; #pragma unroll
;                 for (int bj = 0; bj < 2; ++bj)
; #pragma unroll
;                     for (int n = 0; n < 2; ++n) {
;                         const f32x4 v = acc[ai][bj][m][n];
;                         pq[ai][bj][m][n][0] = r != 0.f ? pk2(v.x * r, v.y * r) : 0u;
;                         pq[ai][bj][m][n][1] = r != 0.f ? pk2(v.z * r, v.w * r) : 0u;
.LBB0_263:
	s_or_b64 exec, exec, s[0:1]
	s_nop 1
	v_mov_b32_e32 v58, v175
	v_mov_b32_e32 v69, 0
	v_mov_b32_e32 v76, 0
	s_waitcnt lgkmcnt(0)
	v_cmp_neq_f32_e32 vcc, 0, v58
	s_and_saveexec_b64 s[0:1], vcc
	s_cbranch_execz .LBB0_265
	v_mul_f32_e32 v55, v55, v58
	v_mul_f32_e32 v54, v54, v58
	v_cvt_pk_bf16_f32 v76, v54, v55

; __device__ __forceinline__ unsigned pk2(float lo, float hi) { unsigned r; asm volatile("v_cvt_pk_bf16_f32 %0, %1, %2" : "=v"(r) : "v"(lo), "v"(hi)); return r; }
;     __device__ __forceinline__ void operator()(f32x4 (&acc)[2][2][4][2], const Unit& u, int wr, int wc, int fr, int fq, LAS unsigned char* lds) const {
;     ...
;             for (int m = 0; m < 4; ++m) {
;                 const float r = rs[128 * ai + 64 * wr + 16 * m + fr];
; #pragma unroll
;                 for (int bj = 0; bj < 2; ++bj)
; #pragma unroll
;                     for (int n = 0; n < 2; ++n) {
;                         const f32x4 v = acc[ai][bj][m][n];
;                         pq[ai][bj][m][n][0] = r != 0.f ? pk2(v.x * r, v.y * r) : 0u;
;                         pq[ai][bj][m][n][1] = r != 0.f ? pk2(v.z * r, v.w * r) : 0u;
.LBB0_279:
	s_or_b64 exec, exec, s[0:1]
	s_nop 1
	v_mov_b32_e32 v46, v176
	v_mov_b32_e32 v15, 0
	v_mov_b32_e32 v14, 0
	s_waitcnt lgkmcnt(0)
	v_cmp_neq_f32_e32 vcc, 0, v46
	s_and_saveexec_b64 s[0:1], vcc
	s_cbranch_execz .LBB0_281
	v_mul_f32_e32 v14, v43, v46
	v_mul_f32_e32 v16, v42, v46
	v_cvt_pk_bf16_f32 v14, v16, v14

; #define LAS __attribute__((address_space(3)))
; __device__ __forceinline__ unsigned pk2(float lo, float hi) { unsigned r; asm volatile("v_cvt_pk_bf16_f32 %0, %1, %2" : "=v"(r) : "v"(lo), "v"(hi)); return r; }
; #define EPI_SYNC() do { asm volatile("s_waitcnt lgkmcnt(0)" ::: "memory"); __builtin_amdgcn_s_barrier(); __builtin_amdgcn_s_barrier(); asm volatile("" ::: "memory"); } while (0)
;     __device__ __forceinline__ void operator()(f32x4 (&acc)[2][2][4][2], const Unit& u, int wr, int wc, int fr, int fq, LAS unsigned char* lds) const {
;     ...
;         EPI_SYNC();
;         const LAS float* rs = (const LAS float*)(lds + EPI_RS);
;         const int row0 = u.pm * 256 + wr * 64 + fr, col0 = wc * 32 + 8 * fq;
; #pragma unroll
;         for (int ai = 0; ai < 2; ++ai)
; #pragma unroll
;             for (int m = 0; m < 4; ++m) {
;                 const int row = row0 + ai * 128 + m * 16; const float r = rs[128 * ai + 64 * wr + 16 * m + fr];
; #pragma unroll
;                 for (int bj = 0; bj < 2; ++bj) {
;                     const f32x4 v0 = acc[ai][bj][m][0] * r, v1 = acc[ai][bj][m][1] * r;
;                     u32x4 o; o.x = pk2(v0.x, v0.y); o.y = pk2(v0.z, v0.w); o.z = pk2(v1.x, v1.y); o.w = pk2(v1.z, v1.w);
;                     *(u32x4*)(Z + (size_t)row * DIN + (bj ? u.b1 : u.b0) + col0) = o;
;                 }
.LBB0_914:
	s_or_b64 exec, exec, s[42:43]
	v_lshlrev_b32_e32 v0, 3, v142
	s_add_i32 s7, s7, 0
	v_lshl_add_u32 v144, s9, 5, v0
	v_lshl_add_u32 v0, v143, 2, s7
	s_waitcnt lgkmcnt(0)
	s_barrier
	s_barrier
	v_add_u32_e32 v0, 0x21000, v0
	ds_read_b32 v146, v0
	ds_read_b32 v232, v0 offset:64
	ds_read_b32 v233, v0 offset:128
	ds_read_b32 v234, v0 offset:192
	ds_read_b32 v235, v0 offset:512
	ds_read_b32 v245, v0 offset:576
	ds_read_b32 v246, v0 offset:640
	ds_read_b32 v247, v0 offset:704
	s_lshl_b32 s37, s40, 8
	v_readlane_b32 s40, v254, 22
	v_readlane_b32 s41, v254, 23
	s_lshl_b32 s11, s11, 6
	s_waitcnt lgkmcnt(0)
	v_pk_mul_f32 v[128:129], v[128:129], v[146:147] op_sel_hi:[1,0]
	v_pk_mul_f32 v[126:127], v[126:127], v[146:147] op_sel_hi:[1,0]
	v_pk_mul_f32 v[124:125], v[124:125], v[146:147] op_sel_hi:[1,0]
	v_pk_mul_f32 v[122:123], v[122:123], v[146:147] op_sel_hi:[1,0]
	v_cvt_pk_bf16_f32 v126, v126, v127
	v_cvt_pk_bf16_f32 v127, v128, v129
	s_add_i32 s11, s11, s37
	v_cvt_pk_bf16_f32 v128, v122, v123
	v_cvt_pk_bf16_f32 v129, v124, v125
	s_load_dwordx2 s[40:41], s[40:41], 0x100
	v_add_u32_e32 v142, s11, v143
	s_ashr_i32 s39, s38, 31
	v_ashrrev_i32_e32 v145, 31, v144
	s_lshl_b64 s[38:39], s[38:39], 1
	s_waitcnt lgkmcnt(0)
	v_mov_b64_e32 v[124:125], s[40:41]
	v_mad_i64_i32 v[148:149], s[40:41], v142, s85, v[124:125]
	v_lshl_add_u64 v[150:151], v[148:149], 0, s[38:39]
	v_lshlrev_b64 v[122:123], 1, v[144:145]
	s_ashr_i32 s37, s36, 31
	v_lshl_add_u64 v[144:145], v[150:151], 0, v[122:123]
	v_pk_mul_f32 v[118:119], v[118:119], v[146:147] op_sel_hi:[1,0]
	s_lshl_b64 s[36:37], s[36:37], 1
	global_store_dwordx4 v[144:145], v[126:129], off
	v_pk_mul_f32 v[120:121], v[120:121], v[146:147] op_sel_hi:[1,0]
	s_and_b64 vcc, exec, s[0:1]
	v_pk_mul_f32 v[126:127], v[116:117], v[146:147] op_sel_hi:[1,0]
	v_pk_mul_f32 v[116:117], v[114:115], v[146:147] op_sel_hi:[1,0]
	v_cvt_pk_bf16_f32 v114, v118, v119
	v_lshl_add_u64 v[118:119], v[148:149], 0, s[36:37]
	v_lshl_add_u64 v[118:119], v[118:119], 0, v[122:123]
	v_cvt_pk_bf16_f32 v115, v120, v121
	v_cvt_pk_bf16_f32 v116, v116, v117
	v_cvt_pk_bf16_f32 v117, v126, v127
	global_store_dwordx4 v[118:119], v[114:117], off
	s_nop 1
	v_mov_b32_e32 v114, v232
	s_mov_b64 s[46:47], s[18:19]
	v_add_u32_e32 v115, 16, v142
	s_mov_b64 s[44:45], s[16:17]
	s_mov_b64 s[42:43], s[14:15]
	s_waitcnt lgkmcnt(0)
	v_pk_mul_f32 v[110:111], v[110:111], v[114:115] op_sel_hi:[1,0]
	v_pk_mul_f32 v[112:113], v[112:113], v[114:115] op_sel_hi:[1,0]
	v_pk_mul_f32 v[116:117], v[108:109], v[114:115] op_sel_hi:[1,0]
	v_pk_mul_f32 v[108:109], v[106:107], v[114:115] op_sel_hi:[1,0]
	v_cvt_pk_bf16_f32 v106, v110, v111
	v_mad_i64_i32 v[110:111], s[40:41], v115, s85, v[124:125]
	v_cvt_pk_bf16_f32 v107, v112, v113
	v_lshl_add_u64 v[112:113], v[110:111], 0, s[38:39]
	v_lshl_add_u64 v[112:113], v[112:113], 0, v[122:123]
	v_pk_mul_f32 v[102:103], v[102:103], v[114:115] op_sel_hi:[1,0]
	v_cvt_pk_bf16_f32 v108, v108, v109
	v_cvt_pk_bf16_f32 v109, v116, v117
	global_store_dwordx4 v[112:113], v[106:109], off
	v_pk_mul_f32 v[104:105], v[104:105], v[114:115] op_sel_hi:[1,0]
	s_nop 0
	v_pk_mul_f32 v[106:107], v[100:101], v[114:115] op_sel_hi:[1,0]
	v_pk_mul_f32 v[100:101], v[98:99], v[114:115] op_sel_hi:[1,0]
	v_cvt_pk_bf16_f32 v98, v102, v103
	v_lshl_add_u64 v[102:103], v[110:111], 0, s[36:37]
	v_lshl_add_u64 v[102:103], v[102:103], 0, v[122:123]
	v_cvt_pk_bf16_f32 v99, v104, v105
	v_cvt_pk_bf16_f32 v100, v100, v101
	v_cvt_pk_bf16_f32 v101, v106, v107
	global_store_dwordx4 v[102:103], v[98:101], off
	s_nop 1
	v_mov_b32_e32 v98, v233
	s_nop 0
	v_add_u32_e32 v99, 32, v142
	s_waitcnt lgkmcnt(0)
	v_pk_mul_f32 v[94:95], v[94:95], v[98:99] op_sel_hi:[1,0]
	v_pk_mul_f32 v[96:97], v[96:97], v[98:99] op_sel_hi:[1,0]
	v_pk_mul_f32 v[100:101], v[92:93], v[98:99] op_sel_hi:[1,0]
	v_pk_mul_f32 v[92:93], v[90:91], v[98:99] op_sel_hi:[1,0]
	v_cvt_pk_bf16_f32 v90, v94, v95
	v_mad_i64_i32 v[94:95], s[40:41], v99, s85, v[124:125]
	v_cvt_pk_bf16_f32 v91, v96, v97
	v_lshl_add_u64 v[96:97], v[94:95], 0, s[38:39]
	v_lshl_add_u64 v[96:97], v[96:97], 0, v[122:123]
	v_pk_mul_f32 v[86:87], v[86:87], v[98:99] op_sel_hi:[1,0]
	v_cvt_pk_bf16_f32 v92, v92, v93
	v_cvt_pk_bf16_f32 v93, v100, v101
	global_store_dwordx4 v[96:97], v[90:93], off
	v_pk_mul_f32 v[88:89], v[88:89], v[98:99] op_sel_hi:[1,0]
	s_nop 0
	v_pk_mul_f32 v[90:91], v[84:85], v[98:99] op_sel_hi:[1,0]
	v_pk_mul_f32 v[84:85], v[82:83], v[98:99] op_sel_hi:[1,0]
	v_cvt_pk_bf16_f32 v82, v86, v87
	v_lshl_add_u64 v[86:87], v[94:95], 0, s[36:37]
	v_lshl_add_u64 v[86:87], v[86:87], 0, v[122:123]
	v_cvt_pk_bf16_f32 v83, v88, v89
	v_cvt_pk_bf16_f32 v84, v84, v85
	v_cvt_pk_bf16_f32 v85, v90, v91
	global_store_dwordx4 v[86:87], v[82:85], off
	s_nop 1
	v_mov_b32_e32 v82, v234
	s_nop 0
	v_add_u32_e32 v83, 48, v142
	s_waitcnt lgkmcnt(0)
; __device__ __forceinline__ unsigned pk2(float lo, float hi) { unsigned r; asm volatile("v_cvt_pk_bf16_f32 %0, %1, %2" : "=v"(r) : "v"(lo), "v"(hi)); return r; }
;     __device__ __forceinline__ void operator()(f32x4 (&acc)[2][2][4][2], const Unit& u, int wr, int wc, int fr, int fq, LAS unsigned char* lds) const {
;     ...
; #pragma unroll
;         for (int ai = 0; ai < 2; ++ai)
; #pragma unroll
;             for (int m = 0; m < 4; ++m) {
;                 const int row = row0 + ai * 128 + m * 16; const float r = rs[128 * ai + 64 * wr + 16 * m + fr];
; #pragma unroll
;                 for (int bj = 0; bj < 2; ++bj) {
;                     const f32x4 v0 = acc[ai][bj][m][0] * r, v1 = acc[ai][bj][m][1] * r;
;                     u32x4 o; o.x = pk2(v0.x, v0.y); o.y = pk2(v0.z, v0.w); o.z = pk2(v1.x, v1.y); o.w = pk2(v1.z, v1.w);
;                     *(u32x4*)(Z + (size_t)row * DIN + (bj ? u.b1 : u.b0) + col0) = o;
;                 }
	v_pk_mul_f32 v[78:79], v[78:79], v[82:83] op_sel_hi:[1,0]
	v_pk_mul_f32 v[80:81], v[80:81], v[82:83] op_sel_hi:[1,0]
	v_pk_mul_f32 v[84:85], v[76:77], v[82:83] op_sel_hi:[1,0]
	v_pk_mul_f32 v[76:77], v[74:75], v[82:83] op_sel_hi:[1,0]
	v_cvt_pk_bf16_f32 v74, v78, v79
	v_mad_i64_i32 v[78:79], s[40:41], v83, s85, v[124:125]
	v_cvt_pk_bf16_f32 v75, v80, v81
	v_lshl_add_u64 v[80:81], v[78:79], 0, s[38:39]
	v_lshl_add_u64 v[80:81], v[80:81], 0, v[122:123]
	v_pk_mul_f32 v[70:71], v[70:71], v[82:83] op_sel_hi:[1,0]
	v_cvt_pk_bf16_f32 v76, v76, v77
	v_cvt_pk_bf16_f32 v77, v84, v85
	global_store_dwordx4 v[80:81], v[74:77], off
	v_pk_mul_f32 v[72:73], v[72:73], v[82:83] op_sel_hi:[1,0]
	s_nop 0
	v_pk_mul_f32 v[74:75], v[68:69], v[82:83] op_sel_hi:[1,0]
	v_pk_mul_f32 v[68:69], v[66:67], v[82:83] op_sel_hi:[1,0]
	v_cvt_pk_bf16_f32 v66, v70, v71
	v_lshl_add_u64 v[70:71], v[78:79], 0, s[36:37]
	v_lshl_add_u64 v[70:71], v[70:71], 0, v[122:123]
	v_cvt_pk_bf16_f32 v67, v72, v73
	v_cvt_pk_bf16_f32 v68, v68, v69
	v_cvt_pk_bf16_f32 v69, v74, v75
	global_store_dwordx4 v[70:71], v[66:69], off
	s_nop 1
	v_mov_b32_e32 v66, v235
	s_nop 0
	v_add_u32_e32 v67, 0x80, v142
	s_waitcnt lgkmcnt(0)
	v_pk_mul_f32 v[62:63], v[62:63], v[66:67] op_sel_hi:[1,0]
	v_pk_mul_f32 v[64:65], v[64:65], v[66:67] op_sel_hi:[1,0]
	v_pk_mul_f32 v[68:69], v[60:61], v[66:67] op_sel_hi:[1,0]
	v_pk_mul_f32 v[60:61], v[58:59], v[66:67] op_sel_hi:[1,0]
	v_cvt_pk_bf16_f32 v58, v62, v63
	v_mad_i64_i32 v[62:63], s[40:41], v67, s85, v[124:125]
	v_cvt_pk_bf16_f32 v59, v64, v65
	v_lshl_add_u64 v[64:65], v[62:63], 0, s[38:39]
	v_lshl_add_u64 v[64:65], v[64:65], 0, v[122:123]
	v_pk_mul_f32 v[54:55], v[54:55], v[66:67] op_sel_hi:[1,0]
	v_cvt_pk_bf16_f32 v60, v60, v61
	v_cvt_pk_bf16_f32 v61, v68, v69
	global_store_dwordx4 v[64:65], v[58:61], off
	v_pk_mul_f32 v[56:57], v[56:57], v[66:67] op_sel_hi:[1,0]
	s_nop 0
	v_pk_mul_f32 v[58:59], v[52:53], v[66:67] op_sel_hi:[1,0]
	v_pk_mul_f32 v[52:53], v[50:51], v[66:67] op_sel_hi:[1,0]
	v_cvt_pk_bf16_f32 v50, v54, v55
	v_lshl_add_u64 v[54:55], v[62:63], 0, s[36:37]
	v_lshl_add_u64 v[54:55], v[54:55], 0, v[122:123]
	v_cvt_pk_bf16_f32 v51, v56, v57
	v_cvt_pk_bf16_f32 v52, v52, v53
	v_cvt_pk_bf16_f32 v53, v58, v59
	global_store_dwordx4 v[54:55], v[50:53], off
	s_nop 1
	v_mov_b32_e32 v50, v245
	s_nop 0
	v_add_u32_e32 v51, 0x90, v142
	s_waitcnt lgkmcnt(0)
	v_pk_mul_f32 v[46:47], v[46:47], v[50:51] op_sel_hi:[1,0]
	v_pk_mul_f32 v[48:49], v[48:49], v[50:51] op_sel_hi:[1,0]
	v_pk_mul_f32 v[52:53], v[44:45], v[50:51] op_sel_hi:[1,0]
	v_pk_mul_f32 v[44:45], v[42:43], v[50:51] op_sel_hi:[1,0]
	v_cvt_pk_bf16_f32 v42, v46, v47
	v_mad_i64_i32 v[46:47], s[40:41], v51, s85, v[124:125]
	v_cvt_pk_bf16_f32 v43, v48, v49
	v_lshl_add_u64 v[48:49], v[46:47], 0, s[38:39]
	v_lshl_add_u64 v[48:49], v[48:49], 0, v[122:123]
	v_pk_mul_f32 v[38:39], v[38:39], v[50:51] op_sel_hi:[1,0]
	v_cvt_pk_bf16_f32 v44, v44, v45
	v_cvt_pk_bf16_f32 v45, v52, v53
	global_store_dwordx4 v[48:49], v[42:45], off
	v_pk_mul_f32 v[40:41], v[40:41], v[50:51] op_sel_hi:[1,0]
	s_nop 0
	v_pk_mul_f32 v[42:43], v[36:37], v[50:51] op_sel_hi:[1,0]
	v_pk_mul_f32 v[36:37], v[34:35], v[50:51] op_sel_hi:[1,0]
	v_cvt_pk_bf16_f32 v34, v38, v39
	v_lshl_add_u64 v[38:39], v[46:47], 0, s[36:37]
	v_lshl_add_u64 v[38:39], v[38:39], 0, v[122:123]
	v_cvt_pk_bf16_f32 v35, v40, v41
	v_cvt_pk_bf16_f32 v36, v36, v37
	v_cvt_pk_bf16_f32 v37, v42, v43
	global_store_dwordx4 v[38:39], v[34:37], off
	s_nop 1
	v_mov_b32_e32 v34, v246
	s_nop 0
	v_add_u32_e32 v35, 0xa0, v142
	s_waitcnt lgkmcnt(0)
	v_pk_mul_f32 v[30:31], v[30:31], v[34:35] op_sel_hi:[1,0]
	v_pk_mul_f32 v[32:33], v[32:33], v[34:35] op_sel_hi:[1,0]
	v_pk_mul_f32 v[36:37], v[28:29], v[34:35] op_sel_hi:[1,0]
	v_pk_mul_f32 v[28:29], v[26:27], v[34:35] op_sel_hi:[1,0]
	v_cvt_pk_bf16_f32 v26, v30, v31
	v_mad_i64_i32 v[30:31], s[40:41], v35, s85, v[124:125]
	v_cvt_pk_bf16_f32 v27, v32, v33
	v_lshl_add_u64 v[32:33], v[30:31], 0, s[38:39]
	v_lshl_add_u64 v[32:33], v[32:33], 0, v[122:123]
	v_cvt_pk_bf16_f32 v28, v28, v29
	v_cvt_pk_bf16_f32 v29, v36, v37
	global_store_dwordx4 v[32:33], v[26:29], off
	v_pk_mul_f32 v[24:25], v[24:25], v[34:35] op_sel_hi:[1,0]
	v_pk_mul_f32 v[22:23], v[22:23], v[34:35] op_sel_hi:[1,0]
	v_pk_mul_f32 v[26:27], v[20:21], v[34:35] op_sel_hi:[1,0]
	v_pk_mul_f32 v[20:21], v[18:19], v[34:35] op_sel_hi:[1,0]
	v_cvt_pk_bf16_f32 v18, v22, v23
	v_cvt_pk_bf16_f32 v19, v24, v25
	v_lshl_add_u64 v[22:23], v[30:31], 0, s[36:37]
	v_cvt_pk_bf16_f32 v20, v20, v21
	v_cvt_pk_bf16_f32 v21, v26, v27
	s_nop 1
	v_mov_b32_e32 v0, v247
	v_lshl_add_u64 v[22:23], v[22:23], 0, v[122:123]
	global_store_dwordx4 v[22:23], v[18:21], off
	s_waitcnt lgkmcnt(0)
	v_pk_mul_f32 v[14:15], v[14:15], v[0:1] op_sel_hi:[1,0]
	v_add_u32_e32 v20, 0xb0, v142
	v_pk_mul_f32 v[16:17], v[16:17], v[0:1] op_sel_hi:[1,0]
	v_pk_mul_f32 v[18:19], v[12:13], v[0:1] op_sel_hi:[1,0]
	v_pk_mul_f32 v[12:13], v[10:11], v[0:1] op_sel_hi:[1,0]
	v_cvt_pk_bf16_f32 v10, v14, v15
	v_mad_i64_i32 v[14:15], s[40:41], v20, s85, v[124:125]
	v_cvt_pk_bf16_f32 v11, v16, v17
	v_lshl_add_u64 v[16:17], v[14:15], 0, s[38:39]
	v_lshl_add_u64 v[16:17], v[16:17], 0, v[122:123]
	v_pk_mul_f32 v[6:7], v[6:7], v[0:1] op_sel_hi:[1,0]
	v_cvt_pk_bf16_f32 v12, v12, v13
	v_cvt_pk_bf16_f32 v13, v18, v19
	global_store_dwordx4 v[16:17], v[10:13], off
	s_mov_b32 s38, s8
	s_mov_b32 s40, s6
	v_pk_mul_f32 v[10:11], v[4:5], v[0:1] op_sel_hi:[1,0]
	v_pk_mul_f32 v[4:5], v[2:3], v[0:1] op_sel_hi:[1,0]
	v_cvt_pk_bf16_f32 v2, v6, v7
	v_lshl_add_u64 v[6:7], v[14:15], 0, s[36:37]
	v_lshl_add_u64 v[6:7], v[6:7], 0, v[122:123]
	s_mov_b32 s36, s10
	v_pk_mul_f32 v[8:9], v[8:9], v[0:1] op_sel_hi:[1,0]
	s_nop 0
	v_cvt_pk_bf16_f32 v3, v8, v9
	v_cvt_pk_bf16_f32 v4, v4, v5
	v_cvt_pk_bf16_f32 v5, v10, v11
	global_store_dwordx4 v[6:7], v[2:5], off
	s_cbranch_vccnz .LBB0_922
